# GQA max-free loop: first QK MFMA of the loop-head step hoisted above the P row-sum VALU (MFMA-first segment head)
# speedup vs baseline: 1.0011x; 1.0011x over previous
.LBB0_292:
	v_mfma_f32_32x32x16_bf16 v[80:95], v[68:71], v[140:143], 0
	v_add_u32_e32 v170, s59, v164
	ds_read_b64_tr_b16 v[172:173], v170 offset:24576
	ds_read_b64_tr_b16 v[174:175], v170 offset:25088
	v_add_f32_e32 v72, v48, v49
	v_add_f32_e32 v72, v50, v72
	v_add_f32_e32 v72, v51, v72
	v_add_f32_e32 v72, v52, v72
	v_add_f32_e32 v72, v53, v72
	v_cvt_pk_bf16_f32 v136, v48, v49
	v_cvt_pk_bf16_f32 v137, v50, v51
	ds_read_b64_tr_b16 v[48:49], v170 offset:28672
	ds_read_b64_tr_b16 v[50:51], v170 offset:29184
	v_add_f32_e32 v68, v54, v72
	v_add_f32_e32 v68, v55, v68
	v_add_f32_e32 v68, v56, v68
	v_add_f32_e32 v112, v57, v68
	s_waitcnt lgkmcnt(10)
	v_mfma_f32_32x32x16_bf16 v[64:79], v[64:67], v[140:143], 0
	v_cvt_pk_bf16_f32 v138, v52, v53
	v_cvt_pk_bf16_f32 v139, v54, v55
	ds_read_b64_tr_b16 v[52:53], v170 offset:25600
	ds_read_b64_tr_b16 v[54:55], v170 offset:26112
	v_add_f32_e32 v112, v58, v112
	v_add_f32_e32 v112, v59, v112
	v_add_f32_e32 v112, v60, v112
	v_add_f32_e32 v112, v61, v112
	v_cvt_pk_bf16_f32 v128, v56, v57
	v_cvt_pk_bf16_f32 v129, v58, v59
	s_waitcnt lgkmcnt(11)
	v_mfma_f32_32x32x16_bf16 v[80:95], v[148:151], v[132:135], v[80:95]
	ds_read_b64_tr_b16 v[56:57], v170 offset:29696
	ds_read_b64_tr_b16 v[58:59], v170 offset:30208
	s_waitcnt lgkmcnt(12)
	v_mfma_f32_32x32x16_bf16 v[64:79], v[144:147], v[132:135], v[64:79]
	v_add_f32_e32 v112, v62, v112
	v_add_f32_e32 v112, v63, v112
	v_add_f32_e32 v112, v32, v112
	v_add_f32_e32 v112, v33, v112
	v_cvt_pk_bf16_f32 v130, v60, v61
	v_cvt_pk_bf16_f32 v131, v62, v63
	ds_read_b64_tr_b16 v[60:61], v170 offset:26624
	ds_read_b64_tr_b16 v[62:63], v170 offset:27136
	s_waitcnt lgkmcnt(13)
	v_mfma_f32_32x32x16_bf16 v[80:95], v[108:111], v[124:127], v[80:95]
	v_add_f32_e32 v108, v34, v112
	v_add_f32_e32 v108, v35, v108
	v_add_f32_e32 v108, v36, v108
	v_add_f32_e32 v108, v37, v108
	v_cvt_pk_bf16_f32 v120, v32, v33
	v_cvt_pk_bf16_f32 v121, v34, v35
	ds_read_b64_tr_b16 v[32:33], v170 offset:30720
	ds_read_b64_tr_b16 v[34:35], v170 offset:31232
	s_waitcnt lgkmcnt(14)
	v_mfma_f32_32x32x16_bf16 v[64:79], v[104:107], v[124:127], v[64:79]
	v_add_f32_e32 v104, v38, v108
	v_add_f32_e32 v104, v39, v104
	v_add_f32_e32 v104, v40, v104
	v_add_f32_e32 v104, v41, v104
	v_cvt_pk_bf16_f32 v122, v36, v37
	v_cvt_pk_bf16_f32 v123, v38, v39
	ds_read_b64_tr_b16 v[36:37], v170 offset:27648
	ds_read_b64_tr_b16 v[38:39], v170 offset:28160
	s_waitcnt lgkmcnt(14)
	v_mfma_f32_32x32x16_bf16 v[80:95], v[100:103], v[116:119], v[80:95]
	v_add_f32_e32 v100, v42, v104
	v_add_f32_e32 v100, v43, v100
	v_add_f32_e32 v100, v44, v100
	v_add_f32_e32 v100, v45, v100
	v_cvt_pk_bf16_f32 v112, v40, v41
	v_cvt_pk_bf16_f32 v113, v42, v43
	ds_read_b64_tr_b16 v[40:41], v170 offset:31744
	ds_read_b64_tr_b16 v[42:43], v170 offset:32256
	v_mfma_f32_32x32x16_bf16 v[64:79], v[96:99], v[116:119], v[64:79]
	v_add_f32_e32 v96, v46, v100
	v_add_f32_e32 v96, v47, v96
	v_add_f32_e32 v170, 0, v96
	v_cvt_pk_bf16_f32 v114, v44, v45
	v_cvt_pk_bf16_f32 v115, v46, v47
	v_lshl_add_u64 v[44:45], v[158:159], 0, s[20:21]
	s_add_i32 s16, s58, s49
	s_mov_b32 s17, m0
	s_mov_b32 m0, s16
	s_nop 0
	global_load_lds_dwordx4 v[44:45], off
	s_mov_b32 m0, s17
	v_lshl_add_u64 v[44:45], v[156:157], 0, s[26:27]
	s_add_i32 s16, s57, s48
	s_mov_b32 s17, m0
	s_mov_b32 m0, s16
	s_nop 0
	global_load_lds_dwordx4 v[44:45], off
	s_mov_b32 m0, s17
	s_waitcnt lgkmcnt(14)
	v_mfma_f32_32x32x16_bf16 v[0:15], v[136:139], v[172:175], v[0:15]
	v_exp_f32_e32 v80, v80
	v_exp_f32_e32 v81, v81
	v_exp_f32_e32 v82, v82
	v_exp_f32_e32 v83, v83
	s_waitcnt lgkmcnt(12)
	v_mfma_f32_32x32x16_bf16 v[16:31], v[136:139], v[48:51], v[16:31]
	v_exp_f32_e32 v84, v84
	v_exp_f32_e32 v85, v85
	v_exp_f32_e32 v86, v86
	v_exp_f32_e32 v87, v87
	v_add_u32_e32 v48, s57, v165
	ds_read_b128 v[44:47], v48
	ds_read_b128 v[100:103], v48 offset:512
	s_waitcnt lgkmcnt(12)
	v_mfma_f32_32x32x16_bf16 v[0:15], v[128:131], v[52:55], v[0:15]
	v_exp_f32_e32 v88, v88
	v_exp_f32_e32 v89, v89
	v_exp_f32_e32 v90, v90
	v_exp_f32_e32 v91, v91
	ds_read_b128 v[104:107], v48 offset:2048
	ds_read_b128 v[108:111], v48 offset:2560
	s_waitcnt lgkmcnt(12)
	v_mfma_f32_32x32x16_bf16 v[16:31], v[128:131], v[56:59], v[16:31]
	v_exp_f32_e32 v92, v92
	v_exp_f32_e32 v93, v93
	v_exp_f32_e32 v94, v94
	v_exp_f32_e32 v95, v95
	ds_read_b128 v[144:147], v48 offset:4096
	ds_read_b128 v[148:151], v48 offset:4608
	s_waitcnt lgkmcnt(12)
	v_mfma_f32_32x32x16_bf16 v[0:15], v[120:123], v[60:63], v[0:15]
	v_exp_f32_e32 v64, v64
	v_exp_f32_e32 v65, v65
	v_exp_f32_e32 v66, v66
	v_exp_f32_e32 v67, v67
	ds_read_b128 v[172:175], v48 offset:6144
	ds_read_b128 v[96:99], v48 offset:6656
	s_waitcnt lgkmcnt(12)
	v_mfma_f32_32x32x16_bf16 v[16:31], v[120:123], v[32:35], v[16:31]
	v_exp_f32_e32 v68, v68
	v_exp_f32_e32 v69, v69
	v_exp_f32_e32 v70, v70
	v_exp_f32_e32 v71, v71
	s_waitcnt lgkmcnt(10)
	v_mfma_f32_32x32x16_bf16 v[0:15], v[112:115], v[36:39], v[0:15]
	v_exp_f32_e32 v72, v72
	v_exp_f32_e32 v73, v73
	v_exp_f32_e32 v74, v74
	v_exp_f32_e32 v75, v75
	s_waitcnt lgkmcnt(8)
	v_mfma_f32_32x32x16_bf16 v[16:31], v[112:115], v[40:43], v[16:31]
	v_exp_f32_e32 v76, v76
	v_exp_f32_e32 v77, v77
	v_exp_f32_e32 v78, v78
	v_exp_f32_e32 v79, v79
	s_waitcnt vmcnt(2) lgkmcnt(0)
	s_barrier
	s_add_i32 s16, s57, 0x2000
	s_cmpk_lg_i32 s57, 0x4000
	s_cselect_b32 s16, s16, 0
	v_add_u32_e32 v171, s58, v164
	ds_read_b64_tr_b16 v[176:177], v171 offset:24576
	ds_read_b64_tr_b16 v[178:179], v171 offset:25088
	s_waitcnt lgkmcnt(9)
	v_mfma_f32_32x32x16_bf16 v[48:63], v[44:47], v[140:143], 0
	v_add_f32_e32 v32, v80, v81
	v_add_f32_e32 v32, v82, v32
	v_add_f32_e32 v32, v83, v32
	v_add_f32_e32 v32, v84, v32
	v_add_f32_e32 v32, v85, v32
	v_cvt_pk_bf16_f32 v136, v80, v81
	v_cvt_pk_bf16_f32 v137, v82, v83
	ds_read_b64_tr_b16 v[80:81], v171 offset:28672
	ds_read_b64_tr_b16 v[82:83], v171 offset:29184
	v_add_f32_e32 v32, v86, v32
	v_add_f32_e32 v32, v87, v32
	v_add_f32_e32 v32, v88, v32
	v_add_f32_e32 v112, v89, v32
	s_waitcnt lgkmcnt(10)
	v_mfma_f32_32x32x16_bf16 v[32:47], v[100:103], v[140:143], 0
	v_cvt_pk_bf16_f32 v138, v84, v85
	v_cvt_pk_bf16_f32 v139, v86, v87
	ds_read_b64_tr_b16 v[84:85], v171 offset:25600
	ds_read_b64_tr_b16 v[86:87], v171 offset:26112
	s_waitcnt lgkmcnt(11)
	v_mfma_f32_32x32x16_bf16 v[48:63], v[104:107], v[132:135], v[48:63]
	v_add_f32_e32 v100, v90, v112
	v_add_f32_e32 v100, v91, v100
	v_add_f32_e32 v100, v92, v100
	v_add_f32_e32 v100, v93, v100
	v_cvt_pk_bf16_f32 v128, v88, v89
	v_cvt_pk_bf16_f32 v129, v90, v91
	ds_read_b64_tr_b16 v[88:89], v171 offset:29696
	ds_read_b64_tr_b16 v[90:91], v171 offset:30208
	s_waitcnt lgkmcnt(12)
	v_mfma_f32_32x32x16_bf16 v[32:47], v[108:111], v[132:135], v[32:47]
	v_add_f32_e32 v100, v94, v100
	v_add_f32_e32 v100, v95, v100
	v_add_f32_e32 v100, v64, v100
	v_add_f32_e32 v100, v65, v100
	v_cvt_pk_bf16_f32 v130, v92, v93
	v_cvt_pk_bf16_f32 v131, v94, v95
	ds_read_b64_tr_b16 v[92:93], v171 offset:26624
	ds_read_b64_tr_b16 v[94:95], v171 offset:27136
	s_waitcnt lgkmcnt(13)
	v_mfma_f32_32x32x16_bf16 v[48:63], v[144:147], v[124:127], v[48:63]
	v_add_f32_e32 v100, v66, v100
	v_add_f32_e32 v100, v67, v100
	v_add_f32_e32 v100, v68, v100
	v_add_f32_e32 v100, v69, v100
	v_cvt_pk_bf16_f32 v120, v64, v65
	v_cvt_pk_bf16_f32 v121, v66, v67
	ds_read_b64_tr_b16 v[180:181], v171 offset:30720
	ds_read_b64_tr_b16 v[182:183], v171 offset:31232
	s_waitcnt lgkmcnt(14)
	v_mfma_f32_32x32x16_bf16 v[32:47], v[148:151], v[124:127], v[32:47]
	v_add_f32_e32 v64, v70, v100
	v_add_f32_e32 v64, v71, v64
	v_add_f32_e32 v64, v72, v64
	v_add_f32_e32 v64, v73, v64
	v_cvt_pk_bf16_f32 v122, v68, v69
	v_cvt_pk_bf16_f32 v123, v70, v71
	ds_read_b64_tr_b16 v[184:185], v171 offset:27648
	ds_read_b64_tr_b16 v[186:187], v171 offset:28160
	s_waitcnt lgkmcnt(14)
	v_mfma_f32_32x32x16_bf16 v[48:63], v[172:175], v[116:119], v[48:63]
	v_add_f32_e32 v64, v74, v64
	v_add_f32_e32 v64, v75, v64
	v_add_f32_e32 v64, v76, v64
	v_add_f32_e32 v64, v77, v64
	v_cvt_pk_bf16_f32 v112, v72, v73
	v_cvt_pk_bf16_f32 v113, v74, v75
	ds_read_b64_tr_b16 v[72:73], v171 offset:31744
	ds_read_b64_tr_b16 v[74:75], v171 offset:32256
	v_mfma_f32_32x32x16_bf16 v[32:47], v[96:99], v[116:119], v[32:47]
	v_add_f32_e32 v64, v78, v64
	v_add_f32_e32 v64, v79, v64
	v_add_f32_e32 v171, 0, v64
	v_cvt_pk_bf16_f32 v114, v76, v77
	v_cvt_pk_bf16_f32 v115, v78, v79
	v_lshl_add_u64 v[64:65], v[158:159], 0, s[28:29]
	s_add_i32 s17, s57, s49
	s_mov_b32 s24, m0
	s_mov_b32 m0, s17
	s_nop 0
	global_load_lds_dwordx4 v[64:65], off
	s_mov_b32 m0, s24
	v_lshl_add_u64 v[156:157], v[156:157], 0, s[22:23]
	s_add_i32 s17, s16, s48
	s_mov_b32 s24, m0
	s_mov_b32 m0, s17
	s_nop 0
	global_load_lds_dwordx4 v[156:157], off
	s_mov_b32 m0, s24
	s_waitcnt lgkmcnt(14)
	v_mfma_f32_32x32x16_bf16 v[0:15], v[136:139], v[176:179], v[0:15]
	v_exp_f32_e32 v48, v48
	v_exp_f32_e32 v49, v49
	v_exp_f32_e32 v50, v50
	v_exp_f32_e32 v51, v51
	s_waitcnt lgkmcnt(12)
	v_mfma_f32_32x32x16_bf16 v[16:31], v[136:139], v[80:83], v[16:31]
	v_exp_f32_e32 v52, v52
	v_exp_f32_e32 v53, v53
	v_exp_f32_e32 v54, v54
	v_exp_f32_e32 v55, v55
	v_add_u32_e32 v76, s16, v165
	ds_read_b128 v[68:71], v76
	ds_read_b128 v[64:67], v76 offset:512
	s_waitcnt lgkmcnt(12)
	v_mfma_f32_32x32x16_bf16 v[0:15], v[128:131], v[84:87], v[0:15]
	v_exp_f32_e32 v56, v56
	v_exp_f32_e32 v57, v57
	v_exp_f32_e32 v58, v58
	v_exp_f32_e32 v59, v59
	ds_read_b128 v[148:151], v76 offset:2048
	ds_read_b128 v[144:147], v76 offset:2560
	s_waitcnt lgkmcnt(12)
	v_mfma_f32_32x32x16_bf16 v[16:31], v[128:131], v[88:91], v[16:31]
	v_exp_f32_e32 v60, v60
	v_exp_f32_e32 v61, v61
	v_exp_f32_e32 v62, v62
	v_exp_f32_e32 v63, v63
	ds_read_b128 v[108:111], v76 offset:4096
	ds_read_b128 v[104:107], v76 offset:4608
	s_waitcnt lgkmcnt(12)
	v_mfma_f32_32x32x16_bf16 v[0:15], v[120:123], v[92:95], v[0:15]
	v_exp_f32_e32 v32, v32
	v_exp_f32_e32 v33, v33
	v_exp_f32_e32 v34, v34
	v_exp_f32_e32 v35, v35
	ds_read_b128 v[100:103], v76 offset:6144
	ds_read_b128 v[96:99], v76 offset:6656
	s_waitcnt lgkmcnt(12)
	v_mfma_f32_32x32x16_bf16 v[16:31], v[120:123], v[180:183], v[16:31]
	v_exp_f32_e32 v36, v36
	v_exp_f32_e32 v37, v37
	v_exp_f32_e32 v38, v38
	v_exp_f32_e32 v39, v39
	s_waitcnt lgkmcnt(10)
	v_mfma_f32_32x32x16_bf16 v[0:15], v[112:115], v[184:187], v[0:15]
	v_exp_f32_e32 v40, v40
	v_exp_f32_e32 v41, v41
	v_exp_f32_e32 v42, v42
	v_exp_f32_e32 v43, v43
	s_waitcnt lgkmcnt(8)
	v_mfma_f32_32x32x16_bf16 v[16:31], v[112:115], v[72:75], v[16:31]
	v_exp_f32_e32 v44, v44
	v_exp_f32_e32 v45, v45
	v_exp_f32_e32 v46, v46
	v_exp_f32_e32 v47, v47
	s_add_i32 s17, s16, 0x2000
	s_waitcnt vmcnt(2) lgkmcnt(0)
	s_barrier
	s_cmpk_lg_i32 s16, 0x4000
	v_add_f32_e32 v72, v167, v170
	s_mov_b32 s59, s57
	s_cselect_b32 s57, s17, 0
	s_add_i32 s56, s56, 2
	v_lshl_add_u64 v[158:159], v[158:159], 0, s[22:23]
	s_mov_b32 s58, s16
	v_add_f32_e32 v167, v72, v171
	s_cmp_gt_u32 s56, 56
	s_cbranch_scc0 .LBB0_292
	s_and_b32 s17, s55, 0x3fffffc0
	s_cmp_lg_u32 0, -1
	s_cselect_b32 s16, 0, 0
	s_add_i32 s24, s16, 0x6000
	s_lshl_b32 s17, s17, 2
	v_add_u32_e32 v72, s24, v168
	s_add_i32 s24, s17, 0
	v_add3_u32 v156, v72, v166, v169
	ds_read_b64_tr_b16 v[168:169], v164 offset:32768
	ds_read_b64_tr_b16 v[170:171], v164 offset:33280
	v_add_f32_e32 v72, v48, v49
	v_add_f32_e32 v72, v50, v72
	v_add_f32_e32 v72, v51, v72
	v_add_f32_e32 v72, v52, v72
	v_add_f32_e32 v72, v53, v72
	v_cvt_pk_bf16_f32 v136, v48, v49
	v_cvt_pk_bf16_f32 v137, v50, v51
	s_waitcnt lgkmcnt(9)
	v_mfma_f32_32x32x16_bf16 v[80:95], v[68:71], v[140:143], 0
	ds_read_b64_tr_b16 v[48:49], v164 offset:36864
	ds_read_b64_tr_b16 v[50:51], v164 offset:37376
	v_add_f32_e32 v68, v54, v72
	v_add_f32_e32 v68, v55, v68
	v_add_f32_e32 v68, v56, v68
	v_add_f32_e32 v112, v57, v68
	v_cvt_pk_bf16_f32 v138, v52, v53
	v_cvt_pk_bf16_f32 v139, v54, v55
	s_waitcnt lgkmcnt(10)
	v_mfma_f32_32x32x16_bf16 v[64:79], v[64:67], v[140:143], 0
	ds_read_b64_tr_b16 v[52:53], v164 offset:33792
	ds_read_b64_tr_b16 v[54:55], v164 offset:34304
	v_add_f32_e32 v112, v58, v112
	v_add_f32_e32 v112, v59, v112
	v_add_f32_e32 v112, v60, v112
	v_add_f32_e32 v112, v61, v112
	v_cvt_pk_bf16_f32 v128, v56, v57
	v_cvt_pk_bf16_f32 v129, v58, v59
	s_waitcnt lgkmcnt(11)
	v_mfma_f32_32x32x16_bf16 v[80:95], v[148:151], v[132:135], v[80:95]
	ds_read_b64_tr_b16 v[56:57], v164 offset:37888
	ds_read_b64_tr_b16 v[58:59], v164 offset:38400
	v_add_f32_e32 v112, v62, v112
	v_add_f32_e32 v112, v63, v112
	v_add_f32_e32 v112, v32, v112
	v_add_f32_e32 v112, v33, v112
	v_cvt_pk_bf16_f32 v130, v60, v61
	v_cvt_pk_bf16_f32 v131, v62, v63
	s_waitcnt lgkmcnt(12)
	v_mfma_f32_32x32x16_bf16 v[64:79], v[144:147], v[132:135], v[64:79]
	ds_read_b64_tr_b16 v[60:61], v164 offset:34816
	ds_read_b64_tr_b16 v[62:63], v164 offset:35328
	s_waitcnt lgkmcnt(13)
	v_mfma_f32_32x32x16_bf16 v[80:95], v[108:111], v[124:127], v[80:95]
	v_add_f32_e32 v108, v34, v112
	v_add_f32_e32 v108, v35, v108
	v_add_f32_e32 v108, v36, v108
	v_add_f32_e32 v108, v37, v108
	v_cvt_pk_bf16_f32 v120, v32, v33
	v_cvt_pk_bf16_f32 v121, v34, v35
	ds_read_b64_tr_b16 v[32:33], v164 offset:38912
	ds_read_b64_tr_b16 v[34:35], v164 offset:39424
	s_waitcnt lgkmcnt(14)
	v_mfma_f32_32x32x16_bf16 v[64:79], v[104:107], v[124:127], v[64:79]
	v_add_f32_e32 v104, v38, v108
	v_add_f32_e32 v104, v39, v104
	v_add_f32_e32 v104, v40, v104
	v_add_f32_e32 v104, v41, v104
	v_cvt_pk_bf16_f32 v122, v36, v37
	v_cvt_pk_bf16_f32 v123, v38, v39
	ds_read_b64_tr_b16 v[36:37], v164 offset:35840
	ds_read_b64_tr_b16 v[38:39], v164 offset:36352
	s_waitcnt lgkmcnt(14)
	v_mfma_f32_32x32x16_bf16 v[80:95], v[100:103], v[116:119], v[80:95]
	v_add_f32_e32 v100, v42, v104
	v_add_f32_e32 v100, v43, v100
	v_add_f32_e32 v100, v44, v100
	v_add_f32_e32 v100, v45, v100
	v_cvt_pk_bf16_f32 v112, v40, v41
	v_cvt_pk_bf16_f32 v113, v42, v43
	ds_read_b64_tr_b16 v[40:41], v164 offset:39936
	ds_read_b64_tr_b16 v[42:43], v164 offset:40448
	v_mfma_f32_32x32x16_bf16 v[64:79], v[96:99], v[116:119], v[64:79]
	v_add_f32_e32 v96, v46, v100
	v_add_f32_e32 v96, v47, v96
	v_add_f32_e32 v96, 0, v96
	v_cvt_pk_bf16_f32 v114, v44, v45
	v_cvt_pk_bf16_f32 v115, v46, v47
	s_add_i32 s16, s16, s54
	v_lshl_add_u64 v[44:45], v[154:155], 0, s[66:67]
	s_add_i32 s17, s16, 0x4000
	s_mov_b32 s25, m0
	s_mov_b32 m0, s17
	s_nop 0
	global_load_lds_dwordx4 v[44:45], off
	s_mov_b32 m0, s25
	s_mov_b64 s[42:43], 0xf00000
	v_lshl_add_u64 v[44:45], v[152:153], 0, s[42:43]
	s_mov_b32 s17, m0
	s_mov_b32 m0, s48
	s_nop 0
	global_load_lds_dwordx4 v[44:45], off
	s_mov_b32 m0, s17
	v_add_f32_e32 v157, v167, v96
	s_waitcnt lgkmcnt(14)
	v_mfma_f32_32x32x16_bf16 v[0:15], v[136:139], v[168:171], v[0:15]
	v_exp_f32_e32 v80, v80
	v_exp_f32_e32 v81, v81
	v_exp_f32_e32 v82, v82
	v_exp_f32_e32 v83, v83
	s_waitcnt lgkmcnt(12)
	v_mfma_f32_32x32x16_bf16 v[16:31], v[136:139], v[48:51], v[16:31]
	v_exp_f32_e32 v84, v84
	v_exp_f32_e32 v85, v85
	v_exp_f32_e32 v86, v86
	v_exp_f32_e32 v87, v87
	ds_read_b128 v[44:47], v165
	ds_read_b128 v[144:147], v165 offset:512
	s_waitcnt lgkmcnt(12)
	v_mfma_f32_32x32x16_bf16 v[0:15], v[128:131], v[52:55], v[0:15]
	v_exp_f32_e32 v88, v88
	v_exp_f32_e32 v89, v89
	v_exp_f32_e32 v90, v90
	v_exp_f32_e32 v91, v91
	ds_read_b128 v[52:55], v165 offset:2048
	ds_read_b128 v[148:151], v165 offset:2560
	s_waitcnt lgkmcnt(12)
	v_mfma_f32_32x32x16_bf16 v[16:31], v[128:131], v[56:59], v[16:31]
	v_exp_f32_e32 v92, v92
	v_exp_f32_e32 v93, v93
	v_exp_f32_e32 v94, v94
	v_exp_f32_e32 v95, v95
	ds_read_b128 v[56:59], v165 offset:4096
	ds_read_b128 v[166:169], v165 offset:4608
	s_waitcnt lgkmcnt(12)
	v_mfma_f32_32x32x16_bf16 v[0:15], v[120:123], v[60:63], v[0:15]
	v_exp_f32_e32 v64, v64
	v_exp_f32_e32 v65, v65
	v_exp_f32_e32 v66, v66
	v_exp_f32_e32 v67, v67
	ds_read_b128 v[60:63], v165 offset:6144
	ds_read_b128 v[48:51], v165 offset:6656
	s_waitcnt lgkmcnt(12)
	v_mfma_f32_32x32x16_bf16 v[16:31], v[120:123], v[32:35], v[16:31]
	v_exp_f32_e32 v68, v68
	v_exp_f32_e32 v69, v69
	v_exp_f32_e32 v70, v70
	v_exp_f32_e32 v71, v71
	s_waitcnt lgkmcnt(10)
	v_mfma_f32_32x32x16_bf16 v[0:15], v[112:115], v[36:39], v[0:15]
	v_exp_f32_e32 v72, v72
	v_exp_f32_e32 v73, v73
	v_exp_f32_e32 v74, v74
	v_exp_f32_e32 v75, v75
	s_waitcnt lgkmcnt(8)
	v_mfma_f32_32x32x16_bf16 v[16:31], v[112:115], v[40:43], v[16:31]
	v_exp_f32_e32 v76, v76
	v_exp_f32_e32 v77, v77
	v_exp_f32_e32 v78, v78
	v_exp_f32_e32 v79, v79
	s_waitcnt vmcnt(2) lgkmcnt(0)
	s_barrier
	ds_read_b64_tr_b16 v[170:171], v164 offset:40960
	ds_read_b64_tr_b16 v[172:173], v164 offset:41472
	v_add_f32_e32 v32, v80, v81
	v_add_f32_e32 v32, v82, v32
	v_add_f32_e32 v32, v83, v32
	v_add_f32_e32 v32, v84, v32
	v_add_f32_e32 v32, v85, v32
	v_cvt_pk_bf16_f32 v136, v80, v81
	v_cvt_pk_bf16_f32 v137, v82, v83
	s_waitcnt lgkmcnt(9)
	v_mfma_f32_32x32x16_bf16 v[96:111], v[44:47], v[140:143], 0
	ds_read_b64_tr_b16 v[80:81], v164 offset:45056
	ds_read_b64_tr_b16 v[82:83], v164 offset:45568
	v_add_f32_e32 v32, v86, v32
	v_add_f32_e32 v32, v87, v32
	v_add_f32_e32 v32, v88, v32
	v_add_f32_e32 v112, v89, v32
	s_waitcnt lgkmcnt(10)
	v_mfma_f32_32x32x16_bf16 v[32:47], v[144:147], v[140:143], 0
	v_cvt_pk_bf16_f32 v138, v84, v85
	v_cvt_pk_bf16_f32 v139, v86, v87
	ds_read_b64_tr_b16 v[84:85], v164 offset:41984
	ds_read_b64_tr_b16 v[86:87], v164 offset:42496
	s_waitcnt lgkmcnt(11)
	v_mfma_f32_32x32x16_bf16 v[96:111], v[52:55], v[132:135], v[96:111]
	v_add_f32_e32 v52, v90, v112
	v_add_f32_e32 v52, v91, v52
	v_add_f32_e32 v52, v92, v52
	v_add_f32_e32 v112, v93, v52
	v_cvt_pk_bf16_f32 v128, v88, v89
	v_cvt_pk_bf16_f32 v129, v90, v91
	ds_read_b64_tr_b16 v[52:53], v164 offset:46080
	ds_read_b64_tr_b16 v[54:55], v164 offset:46592
	s_waitcnt lgkmcnt(12)
	v_mfma_f32_32x32x16_bf16 v[32:47], v[148:151], v[132:135], v[32:47]
	v_add_f32_e32 v88, v94, v112
	v_add_f32_e32 v88, v95, v88
	v_add_f32_e32 v88, v64, v88
	v_add_f32_e32 v112, v65, v88
	v_cvt_pk_bf16_f32 v130, v92, v93
	v_cvt_pk_bf16_f32 v131, v94, v95
	ds_read_b64_tr_b16 v[88:89], v164 offset:43008
	ds_read_b64_tr_b16 v[90:91], v164 offset:43520
	s_waitcnt lgkmcnt(13)
	v_mfma_f32_32x32x16_bf16 v[96:111], v[56:59], v[124:127], v[96:111]
	v_add_f32_e32 v56, v66, v112
	v_add_f32_e32 v56, v67, v56
	v_add_f32_e32 v56, v68, v56
	v_add_f32_e32 v92, v69, v56
	v_cvt_pk_bf16_f32 v120, v64, v65
	v_cvt_pk_bf16_f32 v121, v66, v67
	ds_read_b64_tr_b16 v[56:57], v164 offset:47104
	ds_read_b64_tr_b16 v[58:59], v164 offset:47616
	s_waitcnt lgkmcnt(14)
	v_mfma_f32_32x32x16_bf16 v[32:47], v[166:169], v[124:127], v[32:47]
	v_add_f32_e32 v64, v70, v92
	v_add_f32_e32 v64, v71, v64
	v_add_f32_e32 v64, v72, v64
	v_add_f32_e32 v92, v73, v64
	v_cvt_pk_bf16_f32 v122, v68, v69
	v_cvt_pk_bf16_f32 v123, v70, v71
	ds_read_b64_tr_b16 v[64:65], v164 offset:44032
	ds_read_b64_tr_b16 v[66:67], v164 offset:44544
	s_waitcnt lgkmcnt(14)
	v_mfma_f32_32x32x16_bf16 v[96:111], v[60:63], v[116:119], v[96:111]
	v_add_f32_e32 v60, v74, v92
	v_add_f32_e32 v60, v75, v60
	v_add_f32_e32 v60, v76, v60
	v_add_f32_e32 v68, v77, v60
	v_cvt_pk_bf16_f32 v112, v72, v73
	v_cvt_pk_bf16_f32 v113, v74, v75
	ds_read_b64_tr_b16 v[60:61], v164 offset:48128
	ds_read_b64_tr_b16 v[62:63], v164 offset:48640
	v_mfma_f32_32x32x16_bf16 v[32:47], v[48:51], v[116:119], v[32:47]
	v_add_f32_e32 v48, v78, v68
	v_add_f32_e32 v48, v79, v48
	v_add_f32_e32 v48, 0, v48
	v_cvt_pk_bf16_f32 v114, v76, v77
	v_cvt_pk_bf16_f32 v115, v78, v79
	s_mov_b64 s[42:43], 0xfc0000
	v_add_f32_e32 v157, v157, v48
	v_lshl_add_u64 v[48:49], v[154:155], 0, s[42:43]
	s_mov_b32 s17, m0
	s_mov_b32 m0, s49
	s_nop 0
	global_load_lds_dwordx4 v[48:49], off
	s_mov_b32 m0, s17
	s_mov_b64 s[54:55], 0xf40000
	v_lshl_add_u64 v[48:49], v[152:153], 0, s[54:55]
	s_add_i32 s17, s16, 0x8000
	s_mov_b32 s25, m0
	s_mov_b32 m0, s17
	s_nop 0
	global_load_lds_dwordx4 v[48:49], off
	s_mov_b32 m0, s25
	s_waitcnt lgkmcnt(14)
	v_mfma_f32_32x32x16_bf16 v[0:15], v[136:139], v[170:173], v[0:15]
	v_exp_f32_e32 v96, v96
	v_exp_f32_e32 v97, v97
	v_exp_f32_e32 v98, v98
	v_exp_f32_e32 v99, v99
	s_waitcnt lgkmcnt(12)
	v_mfma_f32_32x32x16_bf16 v[16:31], v[136:139], v[80:83], v[16:31]
	v_exp_f32_e32 v100, v100
	v_exp_f32_e32 v101, v101
	v_exp_f32_e32 v102, v102
	v_exp_f32_e32 v103, v103
	ds_read_b128 v[48:51], v165 offset:8192
	ds_read_b128 v[92:95], v165 offset:8704
	s_waitcnt lgkmcnt(12)
	v_mfma_f32_32x32x16_bf16 v[0:15], v[128:131], v[84:87], v[0:15]
	v_exp_f32_e32 v104, v104
	v_exp_f32_e32 v105, v105
	v_exp_f32_e32 v106, v106
	v_exp_f32_e32 v107, v107
	ds_read_b128 v[84:87], v165 offset:10240
	ds_read_b128 v[144:147], v165 offset:10752
	s_waitcnt lgkmcnt(12)
	v_mfma_f32_32x32x16_bf16 v[16:31], v[128:131], v[52:55], v[16:31]
	v_exp_f32_e32 v108, v108
	v_exp_f32_e32 v109, v109
	v_exp_f32_e32 v110, v110
	v_exp_f32_e32 v111, v111
	ds_read_b128 v[148:151], v165 offset:12288
	ds_read_b128 v[166:169], v165 offset:12800
	s_waitcnt lgkmcnt(12)
	v_mfma_f32_32x32x16_bf16 v[0:15], v[120:123], v[88:91], v[0:15]
	v_exp_f32_e32 v32, v32
	v_exp_f32_e32 v33, v33
	v_exp_f32_e32 v34, v34
	v_exp_f32_e32 v35, v35
	ds_read_b128 v[88:91], v165 offset:14336
	ds_read_b128 v[80:83], v165 offset:14848
	s_waitcnt lgkmcnt(12)
	v_mfma_f32_32x32x16_bf16 v[16:31], v[120:123], v[56:59], v[16:31]
	v_exp_f32_e32 v36, v36
	v_exp_f32_e32 v37, v37
	v_exp_f32_e32 v38, v38
	v_exp_f32_e32 v39, v39
	s_waitcnt lgkmcnt(10)
	v_mfma_f32_32x32x16_bf16 v[0:15], v[112:115], v[64:67], v[0:15]
	v_exp_f32_e32 v40, v40
	v_exp_f32_e32 v41, v41
	v_exp_f32_e32 v42, v42
	v_exp_f32_e32 v43, v43
	s_waitcnt lgkmcnt(8)
	v_mfma_f32_32x32x16_bf16 v[16:31], v[112:115], v[60:63], v[16:31]
	v_exp_f32_e32 v44, v44
	v_exp_f32_e32 v45, v45
	v_exp_f32_e32 v46, v46
	v_exp_f32_e32 v47, v47
	s_waitcnt vmcnt(2) lgkmcnt(0)
	s_barrier
	ds_read_b64_tr_b16 v[170:171], v164 offset:24576
	ds_read_b64_tr_b16 v[172:173], v164 offset:25088
	v_add_f32_e32 v52, v96, v97
	v_add_f32_e32 v52, v98, v52
	v_add_f32_e32 v52, v99, v52
	v_add_f32_e32 v52, v100, v52
	v_add_f32_e32 v52, v101, v52
	v_cvt_pk_bf16_f32 v136, v96, v97
	v_cvt_pk_bf16_f32 v137, v98, v99
	s_waitcnt lgkmcnt(9)
	v_mfma_f32_32x32x16_bf16 v[64:79], v[48:51], v[140:143], 0
	ds_read_b64_tr_b16 v[96:97], v164 offset:28672
	ds_read_b64_tr_b16 v[98:99], v164 offset:29184
	v_add_f32_e32 v48, v102, v52
	v_add_f32_e32 v48, v103, v48
	v_add_f32_e32 v48, v104, v48
	v_add_f32_e32 v112, v105, v48
	v_cvt_pk_bf16_f32 v138, v100, v101
	v_cvt_pk_bf16_f32 v139, v102, v103
	s_waitcnt lgkmcnt(10)
	v_mfma_f32_32x32x16_bf16 v[48:63], v[92:95], v[140:143], 0
	ds_read_b64_tr_b16 v[92:93], v164 offset:25600
	ds_read_b64_tr_b16 v[94:95], v164 offset:26112
	s_waitcnt lgkmcnt(11)
	v_mfma_f32_32x32x16_bf16 v[64:79], v[84:87], v[132:135], v[64:79]
	v_add_f32_e32 v84, v106, v112
	v_add_f32_e32 v84, v107, v84
	v_add_f32_e32 v84, v108, v84
	v_add_f32_e32 v100, v109, v84
	v_cvt_pk_bf16_f32 v128, v104, v105
	v_cvt_pk_bf16_f32 v129, v106, v107
	ds_read_b64_tr_b16 v[84:85], v164 offset:29696
	ds_read_b64_tr_b16 v[86:87], v164 offset:30208
	v_add_f32_e32 v100, v110, v100
	v_add_f32_e32 v100, v111, v100
	v_add_f32_e32 v100, v32, v100
	v_add_f32_e32 v104, v33, v100
	v_cvt_pk_bf16_f32 v130, v108, v109
	v_cvt_pk_bf16_f32 v131, v110, v111
	s_waitcnt lgkmcnt(12)
	v_mfma_f32_32x32x16_bf16 v[48:63], v[144:147], v[132:135], v[48:63]
	ds_read_b64_tr_b16 v[100:101], v164 offset:26624
	ds_read_b64_tr_b16 v[102:103], v164 offset:27136
	v_add_f32_e32 v104, v34, v104
	v_add_f32_e32 v104, v35, v104
	v_add_f32_e32 v104, v36, v104
	v_add_f32_e32 v104, v37, v104
	v_cvt_pk_bf16_f32 v120, v32, v33
	v_cvt_pk_bf16_f32 v121, v34, v35
	s_waitcnt lgkmcnt(13)
	v_mfma_f32_32x32x16_bf16 v[64:79], v[148:151], v[124:127], v[64:79]
	ds_read_b64_tr_b16 v[32:33], v164 offset:30720
	ds_read_b64_tr_b16 v[34:35], v164 offset:31232
	v_add_f32_e32 v104, v38, v104
	v_add_f32_e32 v104, v39, v104
	v_add_f32_e32 v104, v40, v104
	v_add_f32_e32 v104, v41, v104
	v_cvt_pk_bf16_f32 v122, v36, v37
	v_cvt_pk_bf16_f32 v123, v38, v39
	s_waitcnt lgkmcnt(14)
	v_mfma_f32_32x32x16_bf16 v[48:63], v[166:169], v[124:127], v[48:63]
	ds_read_b64_tr_b16 v[36:37], v164 offset:27648
	ds_read_b64_tr_b16 v[38:39], v164 offset:28160
	s_waitcnt lgkmcnt(14)
	v_mfma_f32_32x32x16_bf16 v[64:79], v[88:91], v[116:119], v[64:79]
	v_add_f32_e32 v88, v42, v104
	v_add_f32_e32 v88, v43, v88
	v_add_f32_e32 v88, v44, v88
	v_add_f32_e32 v88, v45, v88
	v_cvt_pk_bf16_f32 v112, v40, v41
	v_cvt_pk_bf16_f32 v113, v42, v43
	ds_read_b64_tr_b16 v[40:41], v164 offset:31744
	ds_read_b64_tr_b16 v[42:43], v164 offset:32256
	v_mfma_f32_32x32x16_bf16 v[48:63], v[80:83], v[116:119], v[48:63]
	v_add_f32_e32 v80, v46, v88
	v_add_f32_e32 v80, v47, v80
	v_add_f32_e32 v80, 0, v80
	v_cvt_pk_bf16_f32 v114, v44, v45
	v_cvt_pk_bf16_f32 v115, v46, v47
	v_lshl_add_u64 v[44:45], v[152:153], 0, s[66:67]
	s_add_i32 s16, s16, 0xa000
	s_mov_b32 s17, m0
	s_mov_b32 m0, s16
	s_nop 0
	global_load_lds_dwordx4 v[44:45], off
	s_mov_b32 m0, s17
	v_add_f32_e32 v154, v157, v80
	s_waitcnt lgkmcnt(14)
	v_mfma_f32_32x32x16_bf16 v[0:15], v[136:139], v[170:173], v[0:15]
	v_exp_f32_e32 v64, v64
	v_exp_f32_e32 v65, v65
	v_exp_f32_e32 v66, v66
	v_exp_f32_e32 v67, v67
	s_waitcnt lgkmcnt(12)
	v_mfma_f32_32x32x16_bf16 v[16:31], v[136:139], v[96:99], v[16:31]
	v_exp_f32_e32 v68, v68
	v_exp_f32_e32 v69, v69
	v_exp_f32_e32 v70, v70
	v_exp_f32_e32 v71, v71
	ds_read_b128 v[44:47], v165 offset:16384
	ds_read_b128 v[104:107], v165 offset:16896
	s_waitcnt lgkmcnt(12)
	v_mfma_f32_32x32x16_bf16 v[0:15], v[128:131], v[92:95], v[0:15]
	v_exp_f32_e32 v72, v72
	v_exp_f32_e32 v73, v73
	v_exp_f32_e32 v74, v74
	v_exp_f32_e32 v75, v75
	ds_read_b128 v[108:111], v165 offset:18432
	ds_read_b128 v[144:147], v165 offset:18944
	s_waitcnt lgkmcnt(12)
	v_mfma_f32_32x32x16_bf16 v[16:31], v[128:131], v[84:87], v[16:31]
	v_exp_f32_e32 v76, v76
	v_exp_f32_e32 v77, v77
	v_exp_f32_e32 v78, v78
	v_exp_f32_e32 v79, v79
	ds_read_b128 v[148:151], v165 offset:20480
	ds_read_b128 v[166:169], v165 offset:20992
	s_waitcnt lgkmcnt(12)
	v_mfma_f32_32x32x16_bf16 v[0:15], v[120:123], v[100:103], v[0:15]
	v_exp_f32_e32 v48, v48
	v_exp_f32_e32 v49, v49
	v_exp_f32_e32 v50, v50
	v_exp_f32_e32 v51, v51
	ds_read_b128 v[100:103], v165 offset:22528
	ds_read_b128 v[96:99], v165 offset:23040
	s_waitcnt lgkmcnt(12)
	v_mfma_f32_32x32x16_bf16 v[16:31], v[120:123], v[32:35], v[16:31]
	v_exp_f32_e32 v52, v52
	v_exp_f32_e32 v53, v53
	v_exp_f32_e32 v54, v54
	v_exp_f32_e32 v55, v55
	s_waitcnt lgkmcnt(10)
	v_mfma_f32_32x32x16_bf16 v[0:15], v[112:115], v[36:39], v[0:15]
	v_exp_f32_e32 v56, v56
	v_exp_f32_e32 v57, v57
	v_exp_f32_e32 v58, v58
	v_exp_f32_e32 v59, v59
	s_waitcnt lgkmcnt(8)
	v_mfma_f32_32x32x16_bf16 v[16:31], v[112:115], v[40:43], v[16:31]
	v_exp_f32_e32 v60, v60
	v_exp_f32_e32 v61, v61
	v_exp_f32_e32 v62, v62
	v_exp_f32_e32 v63, v63
	s_waitcnt vmcnt(1) lgkmcnt(0)
	s_barrier
	ds_read_b64_tr_b16 v[170:171], v164 offset:32768
	ds_read_b64_tr_b16 v[172:173], v164 offset:33280
	v_add_f32_e32 v32, v64, v65
	v_add_f32_e32 v32, v66, v32
	v_add_f32_e32 v32, v67, v32
	v_add_f32_e32 v32, v68, v32
	v_add_f32_e32 v32, v69, v32
	v_cvt_pk_bf16_f32 v136, v64, v65
	v_cvt_pk_bf16_f32 v137, v66, v67
	s_waitcnt lgkmcnt(9)
	v_mfma_f32_32x32x16_bf16 v[80:95], v[44:47], v[140:143], 0
	ds_read_b64_tr_b16 v[64:65], v164 offset:36864
	ds_read_b64_tr_b16 v[66:67], v164 offset:37376
	v_add_f32_e32 v32, v70, v32
	v_add_f32_e32 v32, v71, v32
	v_add_f32_e32 v32, v72, v32
	v_add_f32_e32 v112, v73, v32
	s_waitcnt lgkmcnt(10)
	v_mfma_f32_32x32x16_bf16 v[32:47], v[104:107], v[140:143], 0
	v_cvt_pk_bf16_f32 v138, v68, v69
	v_cvt_pk_bf16_f32 v139, v70, v71
	ds_read_b64_tr_b16 v[68:69], v164 offset:33792
	ds_read_b64_tr_b16 v[70:71], v164 offset:34304
	v_add_f32_e32 v104, v74, v112
	v_add_f32_e32 v104, v75, v104
	v_add_f32_e32 v104, v76, v104
	v_add_f32_e32 v104, v77, v104
	v_cvt_pk_bf16_f32 v128, v72, v73
	v_cvt_pk_bf16_f32 v129, v74, v75
	s_waitcnt lgkmcnt(11)
	v_mfma_f32_32x32x16_bf16 v[80:95], v[108:111], v[132:135], v[80:95]
	ds_read_b64_tr_b16 v[72:73], v164 offset:37888
	ds_read_b64_tr_b16 v[74:75], v164 offset:38400
	s_waitcnt lgkmcnt(12)
	v_mfma_f32_32x32x16_bf16 v[32:47], v[144:147], v[132:135], v[32:47]
	v_add_f32_e32 v104, v78, v104
	v_add_f32_e32 v104, v79, v104
	v_add_f32_e32 v104, v48, v104
	v_add_f32_e32 v104, v49, v104
	v_cvt_pk_bf16_f32 v130, v76, v77
	v_cvt_pk_bf16_f32 v131, v78, v79
	ds_read_b64_tr_b16 v[76:77], v164 offset:34816
	ds_read_b64_tr_b16 v[78:79], v164 offset:35328
	v_add_f32_e32 v104, v50, v104
	v_add_f32_e32 v104, v51, v104
	v_add_f32_e32 v104, v52, v104
	v_add_f32_e32 v104, v53, v104
	v_cvt_pk_bf16_f32 v120, v48, v49
	v_cvt_pk_bf16_f32 v121, v50, v51
	s_waitcnt lgkmcnt(13)
	v_mfma_f32_32x32x16_bf16 v[80:95], v[148:151], v[124:127], v[80:95]
	ds_read_b64_tr_b16 v[48:49], v164 offset:38912
	ds_read_b64_tr_b16 v[50:51], v164 offset:39424
	s_waitcnt lgkmcnt(14)
	v_mfma_f32_32x32x16_bf16 v[32:47], v[166:169], v[124:127], v[32:47]
	v_add_f32_e32 v104, v54, v104
	v_add_f32_e32 v104, v55, v104
	v_add_f32_e32 v104, v56, v104
	v_add_f32_e32 v104, v57, v104
	v_cvt_pk_bf16_f32 v122, v52, v53
	v_cvt_pk_bf16_f32 v123, v54, v55
	ds_read_b64_tr_b16 v[52:53], v164 offset:35840
	ds_read_b64_tr_b16 v[54:55], v164 offset:36352
	s_waitcnt lgkmcnt(14)
	v_mfma_f32_32x32x16_bf16 v[80:95], v[100:103], v[116:119], v[80:95]
	v_add_f32_e32 v100, v58, v104
	v_add_f32_e32 v100, v59, v100
	v_add_f32_e32 v100, v60, v100
	v_add_f32_e32 v100, v61, v100
	v_cvt_pk_bf16_f32 v112, v56, v57
	v_cvt_pk_bf16_f32 v113, v58, v59
	ds_read_b64_tr_b16 v[56:57], v164 offset:39936
	ds_read_b64_tr_b16 v[58:59], v164 offset:40448
	v_mfma_f32_32x32x16_bf16 v[32:47], v[96:99], v[116:119], v[32:47]
	v_add_f32_e32 v96, v62, v100
	v_add_f32_e32 v96, v63, v96
	v_add_f32_e32 v96, 0, v96
	v_cvt_pk_bf16_f32 v114, v60, v61
	v_cvt_pk_bf16_f32 v115, v62, v63
	v_lshl_add_u64 v[60:61], v[152:153], 0, s[42:43]
	s_mov_b32 s16, m0
	s_mov_b32 m0, s48
	s_nop 0
	global_load_lds_dwordx4 v[60:61], off
	s_mov_b32 m0, s16
	v_add_f32_e32 v100, v154, v96
	s_waitcnt lgkmcnt(14)
	v_mfma_f32_32x32x16_bf16 v[0:15], v[136:139], v[170:173], v[0:15]
	v_exp_f32_e32 v80, v80
	v_exp_f32_e32 v81, v81
	v_exp_f32_e32 v82, v82
	v_exp_f32_e32 v83, v83
	s_waitcnt lgkmcnt(12)
	v_mfma_f32_32x32x16_bf16 v[16:31], v[136:139], v[64:67], v[16:31]
	v_exp_f32_e32 v84, v84
	v_exp_f32_e32 v85, v85
	v_exp_f32_e32 v86, v86
	v_exp_f32_e32 v87, v87
	ds_read_b128 v[60:63], v165
	ds_read_b128 v[64:67], v165 offset:512
	s_waitcnt lgkmcnt(12)
	v_mfma_f32_32x32x16_bf16 v[0:15], v[128:131], v[68:71], v[0:15]
	v_exp_f32_e32 v88, v88
	v_exp_f32_e32 v89, v89
	v_exp_f32_e32 v90, v90
	v_exp_f32_e32 v91, v91
	ds_read_b128 v[102:105], v165 offset:2048
	ds_read_b128 v[106:109], v165 offset:2560
	s_waitcnt lgkmcnt(12)
	v_mfma_f32_32x32x16_bf16 v[16:31], v[128:131], v[72:75], v[16:31]
	v_exp_f32_e32 v92, v92
	v_exp_f32_e32 v93, v93
	v_exp_f32_e32 v94, v94
	v_exp_f32_e32 v95, v95
	ds_read_b128 v[144:147], v165 offset:4096
	ds_read_b128 v[148:151], v165 offset:4608
	s_waitcnt lgkmcnt(12)
	v_mfma_f32_32x32x16_bf16 v[0:15], v[120:123], v[76:79], v[0:15]
	v_exp_f32_e32 v32, v32
	v_exp_f32_e32 v33, v33
	v_exp_f32_e32 v34, v34
	v_exp_f32_e32 v35, v35
	ds_read_b128 v[152:155], v165 offset:6144
	ds_read_b128 v[96:99], v165 offset:6656
	s_waitcnt lgkmcnt(12)
	v_mfma_f32_32x32x16_bf16 v[16:31], v[120:123], v[48:51], v[16:31]
	v_exp_f32_e32 v36, v36
	v_exp_f32_e32 v37, v37
	v_exp_f32_e32 v38, v38
	v_exp_f32_e32 v39, v39
	s_waitcnt lgkmcnt(10)
	v_mfma_f32_32x32x16_bf16 v[0:15], v[112:115], v[52:55], v[0:15]
	v_exp_f32_e32 v40, v40
	v_exp_f32_e32 v41, v41
	v_exp_f32_e32 v42, v42
	v_exp_f32_e32 v43, v43
	s_waitcnt lgkmcnt(8)
	v_mfma_f32_32x32x16_bf16 v[16:31], v[112:115], v[56:59], v[16:31]
	v_exp_f32_e32 v44, v44
	v_exp_f32_e32 v45, v45
	v_exp_f32_e32 v46, v46
	v_exp_f32_e32 v47, v47
	s_waitcnt vmcnt(0) lgkmcnt(0)
	s_barrier
	s_mov_b32 s78, 0
	s_cmp_lg_u32 s3, 0x100
	s_cbranch_scc1 .Lgqa_nopf
	s_add_i32 s79, s19, s3
	s_cmpk_gt_i32 s79, 0x9ff
	s_cbranch_scc1 .Lgqa_nopf
	s_add_u32 s80, s76, 0x2000000
	s_addc_u32 s81, s77, 0
	v_lshlrev_b32_e32 v212, 12, v162
	v_lshl_or_b32 v212, v163, 4, v212
	global_load_dwordx4 v[196:199], v212, s[80:81] offset:1536
	global_load_dwordx4 v[200:203], v212, s[80:81] offset:1568
	global_load_dwordx4 v[204:207], v212, s[80:81] offset:1600
	global_load_dwordx4 v[208:211], v212, s[80:81] offset:1632
	s_mov_b32 s78, 1
